# GEMM K-loop: removed 16 no-op s_setprio 0 and 6 duplicate s_waitcnt lgkmcnt(0) per iteration
# speedup vs baseline: 1.0184x; 1.0156x over previous
.LBB0_386:
	s_add_i32 s71, s44, 2
	s_add_u32 s46, s0, 0x80
	s_addc_u32 s45, s1, 0
	s_add_i32 vcc_lo, 0, 0x10000
	v_add_u32_e32 v0, vcc_lo, v224
	s_waitcnt lgkmcnt(0)
	ds_read_b128 v[130:133], v0
	ds_read_b128 v[134:137], v0 offset:1024
	ds_read_b128 v[138:141], v0 offset:2048
	ds_read_b128 v[142:145], v0 offset:3072
	s_cmp_eq_u32 s43, s44
	s_cselect_b32 s44, s72, s46
	s_cselect_b32 s45, s73, s45
	s_cselect_b32 s47, s75, s49
	s_cselect_b32 s46, s74, s48
	v_lshl_add_u64 v[200:201], s[0:1], 0, v[172:173]
	s_add_i32 m0, s98, 0xc000
	ds_read_b128 v[146:149], v229
	ds_read_b128 v[150:153], v229 offset:1024
	ds_read_b128 v[176:179], v229 offset:2048
	ds_read_b128 v[180:183], v229 offset:3072
	ds_read_b128 v[184:187], v229 offset:4096
	ds_read_b128 v[188:191], v229 offset:5120
	ds_read_b128 v[192:195], v229 offset:6144
	ds_read_b128 v[196:199], v229 offset:7168
	global_load_lds_dwordx4 v[200:201], off
	v_lshl_add_u64 v[200:201], s[0:1], 0, v[174:175]
	s_add_i32 m0, s98, 0xe000
	s_nop 0
	global_load_lds_dwordx4 v[200:201], off
	s_waitcnt lgkmcnt(8)
	s_barrier
	s_waitcnt lgkmcnt(0)
	v_mfma_f32_16x16x32_bf16 v[126:129], v[130:133], v[146:149], v[126:129]
	v_mfma_f32_16x16x32_bf16 v[122:125], v[138:141], v[146:149], v[122:125]
	v_mfma_f32_16x16x32_bf16 v[110:113], v[130:133], v[176:179], v[110:113]
	v_mfma_f32_16x16x32_bf16 v[106:109], v[138:141], v[176:179], v[106:109]
	v_mfma_f32_16x16x32_bf16 v[94:97], v[130:133], v[184:187], v[94:97]
	v_mfma_f32_16x16x32_bf16 v[90:93], v[138:141], v[184:187], v[90:93]
	v_mfma_f32_16x16x32_bf16 v[78:81], v[130:133], v[192:195], v[78:81]
	v_mfma_f32_16x16x32_bf16 v[74:77], v[138:141], v[192:195], v[74:77]
	v_mfma_f32_16x16x32_bf16 v[126:129], v[134:137], v[150:153], v[126:129]
	v_mfma_f32_16x16x32_bf16 v[122:125], v[142:145], v[150:153], v[122:125]
	v_mfma_f32_16x16x32_bf16 v[110:113], v[134:137], v[180:183], v[110:113]
	v_mfma_f32_16x16x32_bf16 v[106:109], v[142:145], v[180:183], v[106:109]
	v_mfma_f32_16x16x32_bf16 v[94:97], v[134:137], v[188:191], v[94:97]
	v_mfma_f32_16x16x32_bf16 v[90:93], v[142:145], v[188:191], v[90:93]
	v_mfma_f32_16x16x32_bf16 v[78:81], v[134:137], v[196:199], v[78:81]
	v_mfma_f32_16x16x32_bf16 v[74:77], v[142:145], v[196:199], v[74:77]
	s_barrier
	s_add_i32 vcc_hi, 0, 0x14000
	s_add_i32 vcc_lo, vcc_lo, s97
	v_add_u32_e32 v0, vcc_hi, v224
	v_lshl_add_u64 v[204:205], s[46:47], 0, v[158:159]
	s_mov_b32 m0, vcc_lo
	ds_read_b128 v[200:203], v0
	ds_read_b128 v[230:233], v0 offset:1024
	ds_read_b128 v[234:237], v0 offset:2048
	ds_read_b128 v[238:241], v0 offset:3072
	global_load_lds_dwordx4 v[204:205], off
	v_lshl_add_u64 v[242:243], s[46:47], 0, v[162:163]
	s_add_i32 m0, vcc_lo, 0x2000
	s_nop 0
	global_load_lds_dwordx4 v[242:243], off
	s_barrier
	s_waitcnt lgkmcnt(0)
	v_mfma_f32_16x16x32_bf16 v[118:121], v[200:203], v[146:149], v[118:121]
	v_mfma_f32_16x16x32_bf16 v[114:117], v[234:237], v[146:149], v[114:117]
	v_mfma_f32_16x16x32_bf16 v[102:105], v[200:203], v[176:179], v[102:105]
	v_mfma_f32_16x16x32_bf16 v[98:101], v[234:237], v[176:179], v[98:101]
	v_mfma_f32_16x16x32_bf16 v[86:89], v[200:203], v[184:187], v[86:89]
	v_mfma_f32_16x16x32_bf16 v[82:85], v[234:237], v[184:187], v[82:85]
	v_mfma_f32_16x16x32_bf16 v[70:73], v[200:203], v[192:195], v[70:73]
	v_mfma_f32_16x16x32_bf16 v[66:69], v[234:237], v[192:195], v[66:69]
	v_mfma_f32_16x16x32_bf16 v[118:121], v[230:233], v[150:153], v[118:121]
	v_mfma_f32_16x16x32_bf16 v[114:117], v[238:241], v[150:153], v[114:117]
	v_mfma_f32_16x16x32_bf16 v[102:105], v[230:233], v[180:183], v[102:105]
	v_mfma_f32_16x16x32_bf16 v[98:101], v[238:241], v[180:183], v[98:101]
	v_mfma_f32_16x16x32_bf16 v[86:89], v[230:233], v[188:191], v[86:89]
	v_mfma_f32_16x16x32_bf16 v[82:85], v[238:241], v[188:191], v[82:85]
	v_mfma_f32_16x16x32_bf16 v[70:73], v[230:233], v[196:199], v[70:73]
	v_mfma_f32_16x16x32_bf16 v[66:69], v[238:241], v[196:199], v[66:69]
	s_mov_b32 m0, s98
	v_lshl_add_u64 v[244:245], s[44:45], 0, v[156:157]
	s_barrier
	ds_read_b128 v[146:149], v229 offset:16384
	ds_read_b128 v[150:153], v229 offset:17408
	ds_read_b128 v[176:179], v229 offset:18432
	ds_read_b128 v[180:183], v229 offset:19456
	ds_read_b128 v[184:187], v229 offset:20480
	ds_read_b128 v[188:191], v229 offset:21504
	ds_read_b128 v[192:195], v229 offset:22528
	ds_read_b128 v[196:199], v229 offset:23552
	global_load_lds_dwordx4 v[244:245], off
	v_lshl_add_u64 v[246:247], s[44:45], 0, v[160:161]
	s_mov_b32 m0, s99
	s_nop 0
	global_load_lds_dwordx4 v[246:247], off
	s_barrier
	s_waitcnt lgkmcnt(0)
	v_mfma_f32_16x16x32_bf16 v[62:65], v[130:133], v[146:149], v[62:65]
	v_mfma_f32_16x16x32_bf16 v[58:61], v[138:141], v[146:149], v[58:61]
	v_mfma_f32_16x16x32_bf16 v[46:49], v[130:133], v[176:179], v[46:49]
	v_mfma_f32_16x16x32_bf16 v[42:45], v[138:141], v[176:179], v[42:45]
	v_mfma_f32_16x16x32_bf16 v[30:33], v[130:133], v[184:187], v[30:33]
	v_mfma_f32_16x16x32_bf16 v[26:29], v[138:141], v[184:187], v[26:29]
	v_mfma_f32_16x16x32_bf16 v[14:17], v[130:133], v[192:195], v[14:17]
	v_mfma_f32_16x16x32_bf16 v[10:13], v[138:141], v[192:195], v[10:13]
	v_mfma_f32_16x16x32_bf16 v[62:65], v[134:137], v[150:153], v[62:65]
	v_mfma_f32_16x16x32_bf16 v[58:61], v[142:145], v[150:153], v[58:61]
	v_mfma_f32_16x16x32_bf16 v[46:49], v[134:137], v[180:183], v[46:49]
	v_mfma_f32_16x16x32_bf16 v[42:45], v[142:145], v[180:183], v[42:45]
	v_mfma_f32_16x16x32_bf16 v[30:33], v[134:137], v[188:191], v[30:33]
	v_mfma_f32_16x16x32_bf16 v[26:29], v[142:145], v[188:191], v[26:29]
	v_mfma_f32_16x16x32_bf16 v[14:17], v[134:137], v[196:199], v[14:17]
	v_mfma_f32_16x16x32_bf16 v[10:13], v[142:145], v[196:199], v[10:13]
	s_barrier
	s_add_u32 s46, s46, s95
	s_addc_u32 s47, s47, 0
	s_add_i32 vcc_lo, vcc_hi, s97
	v_lshl_add_u64 v[248:249], s[46:47], 0, v[158:159]
	s_mov_b32 m0, vcc_lo
	v_lshl_add_u64 v[250:251], s[46:47], 0, v[162:163]
	global_load_lds_dwordx4 v[248:249], off
	s_add_i32 m0, vcc_lo, 0x2000
	s_nop 0
	global_load_lds_dwordx4 v[250:251], off
	s_waitcnt vmcnt(6)
	s_barrier
	v_mfma_f32_16x16x32_bf16 v[54:57], v[200:203], v[146:149], v[54:57]
	v_mfma_f32_16x16x32_bf16 v[50:53], v[234:237], v[146:149], v[50:53]
	v_mfma_f32_16x16x32_bf16 v[38:41], v[200:203], v[176:179], v[38:41]
	v_mfma_f32_16x16x32_bf16 v[34:37], v[234:237], v[176:179], v[34:37]
	v_mfma_f32_16x16x32_bf16 v[22:25], v[200:203], v[184:187], v[22:25]
	v_mfma_f32_16x16x32_bf16 v[18:21], v[234:237], v[184:187], v[18:21]
	v_mfma_f32_16x16x32_bf16 v[6:9], v[200:203], v[192:195], v[6:9]
	v_mfma_f32_16x16x32_bf16 v[2:5], v[234:237], v[192:195], v[2:5]
	v_mfma_f32_16x16x32_bf16 v[54:57], v[230:233], v[150:153], v[54:57]
	v_mfma_f32_16x16x32_bf16 v[50:53], v[238:241], v[150:153], v[50:53]
	v_mfma_f32_16x16x32_bf16 v[38:41], v[230:233], v[180:183], v[38:41]
	v_mfma_f32_16x16x32_bf16 v[34:37], v[238:241], v[180:183], v[34:37]
	v_mfma_f32_16x16x32_bf16 v[22:25], v[230:233], v[188:191], v[22:25]
	v_mfma_f32_16x16x32_bf16 v[18:21], v[238:241], v[188:191], v[18:21]
	v_mfma_f32_16x16x32_bf16 v[6:9], v[230:233], v[196:199], v[6:9]
	v_mfma_f32_16x16x32_bf16 v[2:5], v[238:241], v[196:199], v[2:5]
	s_add_i32 s46, 0, 0x18000
	v_add_u32_e32 v0, s46, v224
	s_barrier
	ds_read_b128 v[130:133], v0
	ds_read_b128 v[134:137], v0 offset:1024
	ds_read_b128 v[138:141], v0 offset:2048
	ds_read_b128 v[142:145], v0 offset:3072
	s_add_u32 s44, s44, s20
	s_addc_u32 s45, s45, 0
	s_mov_b32 m0, s94
	v_lshl_add_u64 v[200:201], s[44:45], 0, v[156:157]
	ds_read_b128 v[146:149], v229 offset:32768
	ds_read_b128 v[150:153], v229 offset:33792
	ds_read_b128 v[176:179], v229 offset:34816
	ds_read_b128 v[180:183], v229 offset:35840
	ds_read_b128 v[184:187], v229 offset:36864
	ds_read_b128 v[188:191], v229 offset:37888
	ds_read_b128 v[192:195], v229 offset:38912
	ds_read_b128 v[196:199], v229 offset:39936
	global_load_lds_dwordx4 v[200:201], off
	v_lshl_add_u64 v[200:201], s[44:45], 0, v[160:161]
	s_mov_b32 m0, s65
	s_nop 0
	global_load_lds_dwordx4 v[200:201], off
	s_waitcnt lgkmcnt(8)
	s_barrier
	s_waitcnt lgkmcnt(0)
	v_mfma_f32_16x16x32_bf16 v[126:129], v[130:133], v[146:149], v[126:129]
	v_mfma_f32_16x16x32_bf16 v[122:125], v[138:141], v[146:149], v[122:125]
	v_mfma_f32_16x16x32_bf16 v[110:113], v[130:133], v[176:179], v[110:113]
	v_mfma_f32_16x16x32_bf16 v[106:109], v[138:141], v[176:179], v[106:109]
	v_mfma_f32_16x16x32_bf16 v[94:97], v[130:133], v[184:187], v[94:97]
	v_mfma_f32_16x16x32_bf16 v[90:93], v[138:141], v[184:187], v[90:93]
	v_mfma_f32_16x16x32_bf16 v[78:81], v[130:133], v[192:195], v[78:81]
	v_mfma_f32_16x16x32_bf16 v[74:77], v[138:141], v[192:195], v[74:77]
	v_mfma_f32_16x16x32_bf16 v[126:129], v[134:137], v[150:153], v[126:129]
	v_mfma_f32_16x16x32_bf16 v[122:125], v[142:145], v[150:153], v[122:125]
	v_mfma_f32_16x16x32_bf16 v[110:113], v[134:137], v[180:183], v[110:113]
	v_mfma_f32_16x16x32_bf16 v[106:109], v[142:145], v[180:183], v[106:109]
	v_mfma_f32_16x16x32_bf16 v[94:97], v[134:137], v[188:191], v[94:97]
	v_mfma_f32_16x16x32_bf16 v[90:93], v[142:145], v[188:191], v[90:93]
	v_mfma_f32_16x16x32_bf16 v[78:81], v[134:137], v[196:199], v[78:81]
	v_mfma_f32_16x16x32_bf16 v[74:77], v[142:145], v[196:199], v[74:77]
	s_barrier
	s_add_i32 s44, 0, 0x1c000
	s_add_i32 s45, s46, s97
	v_add_u32_e32 v0, s44, v224
	v_lshl_add_u64 v[204:205], v[204:205], 0, s[22:23]
	s_mov_b32 m0, s45
	ds_read_b128 v[200:203], v0
	ds_read_b128 v[230:233], v0 offset:1024
	ds_read_b128 v[234:237], v0 offset:2048
	ds_read_b128 v[238:241], v0 offset:3072
	global_load_lds_dwordx4 v[204:205], off
	v_lshl_add_u64 v[204:205], v[242:243], 0, s[22:23]
	s_add_i32 m0, s45, 0x2000
	s_nop 0
	global_load_lds_dwordx4 v[204:205], off
	s_barrier
	s_waitcnt lgkmcnt(0)
	v_mfma_f32_16x16x32_bf16 v[118:121], v[200:203], v[146:149], v[118:121]
	v_mfma_f32_16x16x32_bf16 v[114:117], v[234:237], v[146:149], v[114:117]
	v_mfma_f32_16x16x32_bf16 v[102:105], v[200:203], v[176:179], v[102:105]
	v_mfma_f32_16x16x32_bf16 v[98:101], v[234:237], v[176:179], v[98:101]
	v_mfma_f32_16x16x32_bf16 v[86:89], v[200:203], v[184:187], v[86:89]
	v_mfma_f32_16x16x32_bf16 v[82:85], v[234:237], v[184:187], v[82:85]
	v_mfma_f32_16x16x32_bf16 v[70:73], v[200:203], v[192:195], v[70:73]
	v_mfma_f32_16x16x32_bf16 v[66:69], v[234:237], v[192:195], v[66:69]
	v_mfma_f32_16x16x32_bf16 v[118:121], v[230:233], v[150:153], v[118:121]
	v_mfma_f32_16x16x32_bf16 v[114:117], v[238:241], v[150:153], v[114:117]
	v_mfma_f32_16x16x32_bf16 v[102:105], v[230:233], v[180:183], v[102:105]
	v_mfma_f32_16x16x32_bf16 v[98:101], v[238:241], v[180:183], v[98:101]
	v_mfma_f32_16x16x32_bf16 v[86:89], v[230:233], v[188:191], v[86:89]
	v_mfma_f32_16x16x32_bf16 v[82:85], v[238:241], v[188:191], v[82:85]
	v_mfma_f32_16x16x32_bf16 v[70:73], v[230:233], v[196:199], v[70:73]
	v_mfma_f32_16x16x32_bf16 v[66:69], v[238:241], v[196:199], v[66:69]
	s_mov_b32 m0, s87
	v_lshl_add_u64 v[204:205], v[244:245], 0, s[22:23]
	s_barrier
	ds_read_b128 v[146:149], v229 offset:49152
	ds_read_b128 v[150:153], v229 offset:50176
	ds_read_b128 v[176:179], v229 offset:51200
	ds_read_b128 v[180:183], v229 offset:52224
	ds_read_b128 v[184:187], v229 offset:53248
	ds_read_b128 v[188:191], v229 offset:54272
	ds_read_b128 v[192:195], v229 offset:55296
	ds_read_b128 v[196:199], v229 offset:56320
	global_load_lds_dwordx4 v[204:205], off
	v_lshl_add_u64 v[204:205], v[246:247], 0, s[22:23]
	s_mov_b32 m0, s29
	s_nop 0
	global_load_lds_dwordx4 v[204:205], off
	s_barrier
	s_waitcnt lgkmcnt(0)
	v_mfma_f32_16x16x32_bf16 v[62:65], v[130:133], v[146:149], v[62:65]
	v_mfma_f32_16x16x32_bf16 v[58:61], v[138:141], v[146:149], v[58:61]
	v_mfma_f32_16x16x32_bf16 v[46:49], v[130:133], v[176:179], v[46:49]
	v_mfma_f32_16x16x32_bf16 v[42:45], v[138:141], v[176:179], v[42:45]
	v_mfma_f32_16x16x32_bf16 v[30:33], v[130:133], v[184:187], v[30:33]
	v_mfma_f32_16x16x32_bf16 v[26:29], v[138:141], v[184:187], v[26:29]
	v_mfma_f32_16x16x32_bf16 v[14:17], v[130:133], v[192:195], v[14:17]
	v_mfma_f32_16x16x32_bf16 v[10:13], v[138:141], v[192:195], v[10:13]
	v_mfma_f32_16x16x32_bf16 v[62:65], v[134:137], v[150:153], v[62:65]
	v_mfma_f32_16x16x32_bf16 v[58:61], v[142:145], v[150:153], v[58:61]
	v_mfma_f32_16x16x32_bf16 v[46:49], v[134:137], v[180:183], v[46:49]
	v_mfma_f32_16x16x32_bf16 v[42:45], v[142:145], v[180:183], v[42:45]
	v_mfma_f32_16x16x32_bf16 v[30:33], v[134:137], v[188:191], v[30:33]
	v_mfma_f32_16x16x32_bf16 v[26:29], v[142:145], v[188:191], v[26:29]
	v_mfma_f32_16x16x32_bf16 v[14:17], v[134:137], v[196:199], v[14:17]
	v_mfma_f32_16x16x32_bf16 v[10:13], v[142:145], v[196:199], v[10:13]
	s_barrier
	s_add_i32 s44, s44, s97
	v_lshl_add_u64 v[130:131], v[248:249], 0, s[22:23]
	s_mov_b32 m0, s44
	s_nop 0
	global_load_lds_dwordx4 v[130:131], off
	v_lshl_add_u64 v[130:131], v[250:251], 0, s[22:23]
	s_add_i32 m0, s44, 0x2000
	s_nop 0
	global_load_lds_dwordx4 v[130:131], off
	s_waitcnt vmcnt(6)
	s_barrier
	v_mfma_f32_16x16x32_bf16 v[54:57], v[200:203], v[146:149], v[54:57]
	v_mfma_f32_16x16x32_bf16 v[50:53], v[234:237], v[146:149], v[50:53]
	v_mfma_f32_16x16x32_bf16 v[38:41], v[200:203], v[176:179], v[38:41]
	v_mfma_f32_16x16x32_bf16 v[34:37], v[234:237], v[176:179], v[34:37]
	v_mfma_f32_16x16x32_bf16 v[22:25], v[200:203], v[184:187], v[22:25]
	v_mfma_f32_16x16x32_bf16 v[18:21], v[234:237], v[184:187], v[18:21]
	v_mfma_f32_16x16x32_bf16 v[6:9], v[200:203], v[192:195], v[6:9]
	v_mfma_f32_16x16x32_bf16 v[2:5], v[234:237], v[192:195], v[2:5]
	v_mfma_f32_16x16x32_bf16 v[54:57], v[230:233], v[150:153], v[54:57]
	v_mfma_f32_16x16x32_bf16 v[50:53], v[238:241], v[150:153], v[50:53]
	v_mfma_f32_16x16x32_bf16 v[38:41], v[230:233], v[180:183], v[38:41]
	v_mfma_f32_16x16x32_bf16 v[34:37], v[238:241], v[180:183], v[34:37]
	v_mfma_f32_16x16x32_bf16 v[22:25], v[230:233], v[188:191], v[22:25]
	v_mfma_f32_16x16x32_bf16 v[18:21], v[238:241], v[188:191], v[18:21]
	v_mfma_f32_16x16x32_bf16 v[6:9], v[230:233], v[196:199], v[6:9]
	v_mfma_f32_16x16x32_bf16 v[2:5], v[238:241], v[196:199], v[2:5]
	s_add_u32 s0, s0, 0x100
	s_addc_u32 s1, s1, 0
	s_add_u32 s48, s48, 0x100
	s_addc_u32 s49, s49, 0
	s_cmp_ge_i32 s71, s6
	s_mov_b32 s44, s71
	s_barrier
	s_cbranch_scc0 .LBB0_386
	s_lshl_b32 s46, s77, 8
	s_cmp_lt_i32 s64, 1
	s_mov_b64 s[0:1], -1
	s_cbranch_scc1 .LBB0_403
